# attn loop: back-edge rotated - ring-index SALU, pointer increments and exit prep moved under half-2 PV MFMAs; loop head starts directly with QK
# speedup vs baseline: 1.0159x; 1.0029x over previous
; __device__ __forceinline__ void finishSM(f32x16& p0, f32x16& p1, float alpha, float& l_reg, bf16x8& pa0, bf16x8& pa1, bf16x8& pa2, bf16x8& pa3) {
;     ...
;   PK4(p0, 0, pa0); PK4(p0, 8, pa1); PK4(p1, 0, pa2); PK4(p1, 8, pa3);
;     ...
; }
; __device__ __forceinline__ void qkt(f32x16& p0, f32x16& p1, const char* Ks, const bf16x8* qr, const char* qrl, int r32, int hi) {
;   p0 = f32x16{}; p1 = f32x16{};
; #pragma unroll
;   for (int d0 = 0; d0 < 8; ++d0) { int cb = (d0 * 16 + hi * 8) * 2;
;     bf16x8 b0 = *reinterpret_cast<const bf16x8*>(Ks + KSWZ(r32, cb));
;     bf16x8 b1 = *reinterpret_cast<const bf16x8*>(Ks + KSWZ(32 + r32, cb));
;     p0 = __builtin_amdgcn_mfma_f32_32x32x16_bf16(b0, qr[d0], p0, 0, 0, 0);
;     p1 = __builtin_amdgcn_mfma_f32_32x32x16_bf16(b1, qr[d0], p1, 0, 0, 0); }
; #pragma unroll
;   for (int d0 = 8; d0 < 12; ++d0) { int cb = (d0 * 16 + hi * 8) * 2;
;     bf16x8 b0 = *reinterpret_cast<const bf16x8*>(Ks + KSWZ(r32, cb));
;     bf16x8 b1 = *reinterpret_cast<const bf16x8*>(Ks + KSWZ(32 + r32, cb));
;     bf16x8 qf = *reinterpret_cast<const bf16x8*>(qrl + (((2 * (d0 - 8) + hi) ^ ((r32 >> 1) & 7)) << 4));
;     p0 = __builtin_amdgcn_mfma_f32_32x32x16_bf16(b0, qf, p0, 0, 0, 0);
;     p1 = __builtin_amdgcn_mfma_f32_32x32x16_bf16(b1, qf, p1, 0, 0, 0); }
; }
; __device__ __forceinline__ int v_st(int k, int c) { const int kk = (k & ~0xC) | ((k & 4) << 1) | ((k & 8) >> 1); return ((kk >> 3) * 4 + (c >> 5)) * 512 + ((kk & 7) * 32 + (c & 31)) * 2; }
; __device__ __forceinline__ int v_rd_base(int lane) { return ((lane & 3) << 3) | (((lane >> 2) & 3) << 6) | (((lane >> 4) & 1) << 5) | (((lane >> 5) & 1) << 8); }
; template <int OFF> __device__ __forceinline__ s16x4 tr_read(int vb) {
;   s16x4 r; asm volatile("ds_read_b64_tr_b16 %0, %1 offset:%2" : "=&v"(r) : "v"(vb), "i"(OFF) : "memory"); return r;
; }
; template <int D0> __device__ __forceinline__ void pv_one(f32x16& od, int vb, bf16x8 pa0, bf16x8 pa1, bf16x8 pa2, bf16x8 pa3) {
;   const s16x4 l0 = tr_read<v_rd_off(D0, 0, 0)>(vb), h0 = tr_read<v_rd_off(D0, 0, 1)>(vb), l1 = tr_read<v_rd_off(D0, 1, 0)>(vb), h1 = tr_read<v_rd_off(D0, 1, 1)>(vb);
;   const s16x4 l2 = tr_read<v_rd_off(D0, 2, 0)>(vb), h2 = tr_read<v_rd_off(D0, 2, 1)>(vb), l3 = tr_read<v_rd_off(D0, 3, 0)>(vb), h3 = tr_read<v_rd_off(D0, 3, 1)>(vb);
;   asm volatile("s_waitcnt lgkmcnt(0)" ::: "memory"); SBAR();
.Lattn_noloadp:
	s_waitcnt lgkmcnt(3)
	v_mfma_f32_32x32x16_bf16 v[80:95], v[232:235], v[240:243], v[80:95]
	ds_read_b128 v[232:235], v179
	v_cvt_pk_bf16_f32 v158, v158, v159
	v_cvt_pk_bf16_f32 v159, v156, v157
	v_permlane32_swap_b32_e32 v211, v212
	v_cvt_pk_bf16_f32 v156, v162, v163
	v_cvt_pk_bf16_f32 v157, v160, v161
	v_cvt_pk_bf16_f32 v160, v154, v155
	v_mfma_f32_32x32x16_bf16 v[64:79], v[236:239], v[240:243], v[64:79]
	ds_read_b128 v[236:239], v188 offset:12288
	ds_read_b128 v[240:243], v190 offset:24576
	v_cvt_pk_bf16_f32 v161, v152, v153
	v_cvt_pk_bf16_f32 v162, v150, v151
	v_cvt_pk_bf16_f32 v163, v148, v149
	v_add_f32_e32 v211, v211, v212
	v_cvt_pk_bf16_f32 v148, v225, v228
	v_cvt_pk_bf16_f32 v149, v226, v229
	s_waitcnt lgkmcnt(2)
	v_mfma_f32_32x32x16_bf16 v[80:95], v[248:251], v[232:235], v[80:95]
	ds_read_b128 v[248:251], v177
	v_cvt_pk_bf16_f32 v150, v227, v230
	v_cvt_pk_bf16_f32 v151, v223, v224
	v_cvt_pk_bf16_f32 v152, v219, v221
	v_cvt_pk_bf16_f32 v153, v220, v222
	v_cvt_pk_bf16_f32 v154, v215, v217
	v_cvt_pk_bf16_f32 v155, v216, v218
	v_mfma_f32_32x32x16_bf16 v[64:79], v[244:247], v[232:235], v[64:79]
	v_fma_f32 v176, v214, v176, v211
	s_waitcnt lgkmcnt(0)
	v_mfma_f32_32x32x16_bf16 v[80:95], v[236:239], v[248:251], v[80:95]
	v_mfma_f32_32x32x16_bf16 v[64:79], v[240:243], v[248:251], v[64:79]
	v_lshl_add_u32 v231, s76, 14, v178
	ds_read_b64_tr_b16 v[232:233], v231 offset:0
	ds_read_b64_tr_b16 v[234:235], v231 offset:2048
	ds_read_b64_tr_b16 v[236:237], v231 offset:512
	ds_read_b64_tr_b16 v[238:239], v231 offset:2560
	ds_read_b64_tr_b16 v[240:241], v231 offset:1024
	ds_read_b64_tr_b16 v[242:243], v231 offset:3072
	ds_read_b64_tr_b16 v[248:249], v231 offset:1536
	ds_read_b64_tr_b16 v[250:251], v231 offset:3584
	ds_read_b64_tr_b16 v[244:245], v231 offset:4096
	ds_read_b64_tr_b16 v[246:247], v231 offset:6144
	s_nop 3
	s_mov_b64 s[100:101], 0x4000
	v_lshl_add_u64 v[166:167], v[166:167], 0, s[100:101]
	v_lshl_add_u64 v[168:169], v[168:169], 0, s[10:11]
	v_max3_f32 v194, v80, v81, v82
	v_max3_f32 v195, v64, v65, v66
	s_waitcnt lgkmcnt(6)
	v_mfma_f32_32x32x16_bf16 v[32:47], v[148:151], v[232:235], v[32:47]
	ds_read_b64_tr_b16 v[232:233], v231 offset:4608
	ds_read_b64_tr_b16 v[234:235], v231 offset:6656
	v_max3_f32 v194, v194, v83, v84
	v_max3_f32 v195, v195, v67, v68
	v_max3_f32 v194, v194, v85, v86
	v_max3_f32 v195, v195, v69, v70
	v_mfma_f32_32x32x16_bf16 v[48:63], v[148:151], v[236:239], v[48:63]
	ds_read_b64_tr_b16 v[236:237], v231 offset:5120
	ds_read_b64_tr_b16 v[238:239], v231 offset:7168
	v_max3_f32 v194, v194, v87, v88
	v_max3_f32 v195, v195, v71, v72
	v_max3_f32 v194, v194, v89, v90
	v_max3_f32 v195, v195, v73, v74
	s_waitcnt lgkmcnt(6)
	v_mfma_f32_32x32x16_bf16 v[16:31], v[148:151], v[240:243], v[16:31]
	ds_read_b64_tr_b16 v[240:241], v231 offset:5632
	ds_read_b64_tr_b16 v[242:243], v231 offset:7680
	v_max3_f32 v194, v194, v91, v92
	v_max3_f32 v195, v195, v75, v76
	v_max3_f32 v194, v194, v93, v94
	v_max3_f32 v195, v195, v77, v78
	v_mfma_f32_32x32x16_bf16 v[0:15], v[148:151], v[248:251], v[0:15]
	ds_read_b64_tr_b16 v[248:249], v231 offset:8192
	ds_read_b64_tr_b16 v[250:251], v231 offset:10240
	v_max3_f32 v194, v194, v95, v195
	v_max_f32_e32 v194, v194, v79
	v_mov_b32_e32 v195, v194
	s_nop 1
	s_waitcnt lgkmcnt(6)
	v_mfma_f32_32x32x16_bf16 v[32:47], v[152:155], v[244:247], v[32:47]
	ds_read_b64_tr_b16 v[244:245], v231 offset:8704
	ds_read_b64_tr_b16 v[246:247], v231 offset:10752
	v_permlane32_swap_b32_e32 v194, v195
	v_max_f32_e32 v194, v194, v195
	v_sub_f32_e32 v195, v194, v210
	v_cmp_ge_f32_e32 vcc, s15, v195
	v_mfma_f32_32x32x16_bf16 v[48:63], v[152:155], v[232:235], v[48:63]
	ds_read_b64_tr_b16 v[232:233], v231 offset:9216
	ds_read_b64_tr_b16 v[234:235], v231 offset:11264
	s_cmp_eq_u64 vcc, exec
	s_cselect_b64 s[40:41], -1, 0
	s_cbranch_scc1 .Lattn_fast2p
	v_max_f32_e32 v194, v210, v194
	v_sub_f32_e32 v195, v210, v194
	v_mul_f32_e32 v195, 0x3dd53b94, v195
	v_exp_f32_e32 v213, v195
	v_mov_b32_e32 v210, v194
	s_branch .Lattn_join2p

; #define SBAR() __builtin_amdgcn_sched_barrier(0)
; #define RESC(a) do { if (__any((a) < 1.f)) { if (hi == 0) al_l[r32] = (a); asm volatile("s_waitcnt lgkmcnt(0)" ::: "memory"); \
;     _Pragma("unroll") for (int d = 0; d < 4; ++d) _Pragma("unroll") for (int r = 0; r < 16; ++r) o[d][r] *= al_l[crow(r, hi)]; } } while (0)
; #define LBAR() do { asm volatile("s_waitcnt lgkmcnt(0)" ::: "memory"); __builtin_amdgcn_s_barrier(); asm volatile("" ::: "memory"); } while (0)
; __device__ __forceinline__ void partialSM(f32x16& p0, f32x16& p1, float& m_reg, float& mn, float& alpha) {
;     ...
;   float mnC = -mn * C;
; #pragma unroll
;   for (int r = 0; r < 16; ++r) p0[r] = fmaf(p0[r], C, mnC);
; #pragma unroll
;   for (int r = 0; r < 16; ++r) p1[r] = fmaf(p1[r], C, mnC);
; __device__ __forceinline__ void attn_unit(const bf16_t* __restrict__ Qb, const bf16_t* __restrict__ Kn, const bf16_t* __restrict__ Vh, const bf16_t* __restrict__ Kr,
;                                           bf16_t* GO, int seq, char* lds, const int tid) {
;     ...
;   f32x16 pA0, pA1, pB0, pB1; float mnA, mnB, alA, alB; bf16x8 pa0, pa1, pa2, pa3; const int NT = seq / KVBLK;
;     ...
;   SLOAD(0, 0); SWRITE(0, 0); SLOAD(0, KVBLK); LBAR();
;   qkt(pA0, pA1, K_lds, qr, qrl, r32, hi); partialSM(pA0, pA1, m_reg, mnA, alA);
;   SWRITE(1, 0); if (2 < NT) SLOAD(0, 2 * KVBLK); LBAR();
;   int bc = 1;
;   for (int j = 1; j + 1 < NT; j += 2) {
;     const int bp = bc == 0 ? 2 : bc - 1, bn = bc == 2 ? 0 : bc + 1;
;     SBAR(); qkt(pB0, pB1, K_lds + bc * SHM_K, qr, qrl, r32, hi);
;     finishSM(pA0, pA1, alA, l_reg, pa0, pa1, pa2, pa3); SBAR();
;     SWRITE(bn, 0); SLOAD(0, (j + 2) * KVBLK); SBAR();
;     pv_d0(o, vb0 + bp * SHM_V, pa0, pa1, pa2, pa3); partialSM(pB0, pB1, m_reg, mnB, alB);
;     RESC(alB); LBAR();
;     SBAR(); qkt(pA0, pA1, K_lds + bn * SHM_K, qr, qrl, r32, hi);
;     finishSM(pB0, pB1, alB, l_reg, pa0, pa1, pa2, pa3); SBAR();
;     SWRITE(bp, 0); if (j + 3 < NT) SLOAD(0, (j + 3) * KVBLK); SBAR();
;     pv_d0(o, vb0 + bc * SHM_V, pa0, pa1, pa2, pa3); partialSM(pA0, pA1, m_reg, mnA, alA);
;     RESC(alA); LBAR();
;     bc = bp;
.Lattn_join2p:
	v_mul_f32_e32 v194, 0xbdd53b94, v210
	s_waitcnt lgkmcnt(6)
	v_mfma_f32_32x32x16_bf16 v[16:31], v[152:155], v[236:239], v[16:31]
	ds_read_b64_tr_b16 v[236:237], v231 offset:9728
	ds_read_b64_tr_b16 v[238:239], v231 offset:11776
	s_sub_i32 s100, s30, 1
	s_cmp_eq_u32 s30, 0
	s_cselect_b32 s100, 2, s100
	s_add_i32 s101, s30, 1
	s_cmp_lg_u32 s30, 2
	s_cselect_b32 s101, s101, 0
	s_movk_i32 s34, 0x6000
	v_fmamk_f32 v225, v80, 0x3dd53b94, v194
	v_fmamk_f32 v228, v81, 0x3dd53b94, v194
	v_fmamk_f32 v226, v82, 0x3dd53b94, v194
	v_mfma_f32_32x32x16_bf16 v[0:15], v[152:155], v[240:243], v[0:15]
	ds_read_b64_tr_b16 v[240:241], v231 offset:12288
	ds_read_b64_tr_b16 v[242:243], v231 offset:14336
	v_fmamk_f32 v229, v83, 0x3dd53b94, v194
	v_fmamk_f32 v150, v76, 0x3dd53b94, v194
	v_fmamk_f32 v151, v77, 0x3dd53b94, v194
	v_fmamk_f32 v148, v78, 0x3dd53b94, v194
	s_waitcnt lgkmcnt(6)
	v_mfma_f32_32x32x16_bf16 v[32:47], v[156:159], v[248:251], v[32:47]
	ds_read_b64_tr_b16 v[248:249], v231 offset:12800
	ds_read_b64_tr_b16 v[250:251], v231 offset:14848
	v_fmamk_f32 v149, v79, 0x3dd53b94, v194
	v_fmamk_f32 v227, v84, 0x3dd53b94, v194
	v_fmamk_f32 v230, v85, 0x3dd53b94, v194
	v_fmamk_f32 v223, v86, 0x3dd53b94, v194
	v_mfma_f32_32x32x16_bf16 v[48:63], v[156:159], v[244:247], v[48:63]
	ds_read_b64_tr_b16 v[244:245], v231 offset:13312
	ds_read_b64_tr_b16 v[246:247], v231 offset:15360
	v_fmamk_f32 v224, v87, 0x3dd53b94, v194
	v_fmamk_f32 v154, v72, 0x3dd53b94, v194
	v_fmamk_f32 v155, v73, 0x3dd53b94, v194
	v_fmamk_f32 v152, v74, 0x3dd53b94, v194
	s_waitcnt lgkmcnt(6)
	v_mfma_f32_32x32x16_bf16 v[16:31], v[156:159], v[232:235], v[16:31]
	ds_read_b64_tr_b16 v[232:233], v231 offset:13824
	ds_read_b64_tr_b16 v[234:235], v231 offset:15872
	v_fmamk_f32 v153, v75, 0x3dd53b94, v194
	v_fmamk_f32 v219, v88, 0x3dd53b94, v194
	v_fmamk_f32 v221, v89, 0x3dd53b94, v194
	v_fmamk_f32 v220, v90, 0x3dd53b94, v194
	v_mfma_f32_32x32x16_bf16 v[0:15], v[156:159], v[236:239], v[0:15]
	v_fmamk_f32 v222, v91, 0x3dd53b94, v194
	v_fmamk_f32 v158, v68, 0x3dd53b94, v194
	v_fmamk_f32 v159, v69, 0x3dd53b94, v194
	v_fmamk_f32 v156, v70, 0x3dd53b94, v194
	s_waitcnt lgkmcnt(0)
	s_barrier
	ds_read_b128 v[236:239], v199 offset:36864
	v_mfma_f32_32x32x16_bf16 v[32:47], v[160:163], v[240:243], v[32:47]
	ds_read_b128 v[240:243], v199 offset:49152
	v_fmamk_f32 v157, v71, 0x3dd53b94, v194
	v_fmamk_f32 v215, v92, 0x3dd53b94, v194
	v_fmamk_f32 v217, v93, 0x3dd53b94, v194
	v_fmamk_f32 v216, v94, 0x3dd53b94, v194
	v_mfma_f32_32x32x16_bf16 v[48:63], v[160:163], v[248:251], v[48:63]
	ds_read_b128 v[248:251], v205 offset:36864
	v_fmamk_f32 v218, v95, 0x3dd53b94, v194
	v_mfma_f32_32x32x16_bf16 v[16:31], v[160:163], v[244:247], v[16:31]
	ds_read_b128 v[244:247], v205 offset:49152
	v_mfma_f32_32x32x16_bf16 v[0:15], v[160:163], v[232:235], v[0:15]
	ds_read_b128 v[232:235], v206 offset:36864
	v_fmamk_f32 v162, v64, 0x3dd53b94, v194
	v_fmamk_f32 v163, v65, 0x3dd53b94, v194
	v_fmamk_f32 v160, v66, 0x3dd53b94, v194
	v_fmamk_f32 v161, v67, 0x3dd53b94, v194
	s_and_b64 vcc, exec, s[40:41]
	s_cbranch_vccnz .Lattn_skip_rs2p
	s_and_saveexec_b64 s[18:19], s[38:39]
	ds_write_b32 v175, v213 offset:128
	s_or_b64 exec, exec, s[18:19]
	s_waitcnt lgkmcnt(0)
	v_add_u32_e32 v194, v173, v164
	ds_read_b128 v[64:67], v194 offset:224
	ds_read_b128 v[68:71], v194 offset:192
	ds_read_b128 v[72:75], v194 offset:160
	ds_read_b128 v[76:79], v194 offset:128
	s_waitcnt lgkmcnt(0)
	v_pk_mul_f32 v[44:45], v[44:45], v[64:65]
	v_pk_mul_f32 v[46:47], v[46:47], v[66:67]
	v_pk_mul_f32 v[40:41], v[40:41], v[68:69]
	v_pk_mul_f32 v[42:43], v[42:43], v[70:71]
	v_pk_mul_f32 v[36:37], v[36:37], v[72:73]
	v_pk_mul_f32 v[38:39], v[38:39], v[74:75]
	v_pk_mul_f32 v[32:33], v[32:33], v[76:77]
	v_pk_mul_f32 v[34:35], v[34:35], v[78:79]
	v_pk_mul_f32 v[60:61], v[60:61], v[64:65]
	v_pk_mul_f32 v[62:63], v[62:63], v[66:67]
	v_pk_mul_f32 v[56:57], v[56:57], v[68:69]
	v_pk_mul_f32 v[58:59], v[58:59], v[70:71]
	v_pk_mul_f32 v[52:53], v[52:53], v[72:73]
	v_pk_mul_f32 v[54:55], v[54:55], v[74:75]
	v_pk_mul_f32 v[48:49], v[48:49], v[76:77]
	v_pk_mul_f32 v[50:51], v[50:51], v[78:79]
	v_pk_mul_f32 v[28:29], v[28:29], v[64:65]
	v_pk_mul_f32 v[30:31], v[30:31], v[66:67]
	v_pk_mul_f32 v[24:25], v[24:25], v[68:69]
	v_pk_mul_f32 v[26:27], v[26:27], v[70:71]
	v_pk_mul_f32 v[20:21], v[20:21], v[72:73]
	v_pk_mul_f32 v[22:23], v[22:23], v[74:75]
	v_pk_mul_f32 v[16:17], v[16:17], v[76:77]
	v_pk_mul_f32 v[18:19], v[18:19], v[78:79]
	v_pk_mul_f32 v[12:13], v[12:13], v[64:65]
	v_pk_mul_f32 v[14:15], v[14:15], v[66:67]
	v_pk_mul_f32 v[8:9], v[8:9], v[68:69]
	v_pk_mul_f32 v[10:11], v[10:11], v[70:71]
	v_pk_mul_f32 v[4:5], v[4:5], v[72:73]
	v_pk_mul_f32 v[6:7], v[6:7], v[74:75]
	v_pk_mul_f32 v[0:1], v[0:1], v[76:77]
	v_pk_mul_f32 v[2:3], v[2:3], v[78:79]
.Lattn_skip_rs2p:
	s_and_b64 vcc, exec, s[28:29]
	s_cbranch_vccnz .LBB0_1163
	s_mov_b32 s76, s30
	s_mov_b32 s30, s100
	s_mov_b32 s18, s101
	v_mov_b32_e32 v209, v213
; __device__ __forceinline__ void partialSM(f32x16& p0, f32x16& p1, float& m_reg, float& mn, float& alpha) {
;     ...
;   for (int r = 0; r < 16; ++r) p0[r] = __builtin_amdgcn_exp2f(p0[r]);
; }
; __device__ __forceinline__ void finishSM(f32x16& p0, f32x16& p1, float alpha, float& l_reg, bf16x8& pa0, bf16x8& pa1, bf16x8& pa2, bf16x8& pa3) {
; #pragma unroll
;   for (int r = 0; r < 16; ++r) p1[r] = __builtin_amdgcn_exp2f(p1[r]);
;   float ps = 0;
; #pragma unroll
;   for (int r = 0; r < 16; ++r) ps += p0[r];
; #pragma unroll
;   for (int r = 0; r < 16; ++r) ps += p1[r];
;   { auto rr = __builtin_amdgcn_permlane32_swap(__float_as_uint(ps), __float_as_uint(ps), false, false);
;     ps = __uint_as_float(rr[0]) + __uint_as_float(rr[1]); }
;   l_reg = l_reg * alpha + ps;
;     ...
;   PK4(p0, 0, pa0); PK4(p0, 8, pa1); PK4(p1, 0, pa2); PK4(p1, 8, pa3);
;     ...
; }
; __device__ __forceinline__ void qkt(f32x16& p0, f32x16& p1, const char* Ks, const bf16x8* qr, const char* qrl, int r32, int hi) {
;   p0 = f32x16{}; p1 = f32x16{};
; #pragma unroll
;   for (int d0 = 0; d0 < 8; ++d0) { int cb = (d0 * 16 + hi * 8) * 2;
;     bf16x8 b0 = *reinterpret_cast<const bf16x8*>(Ks + KSWZ(r32, cb));
;     bf16x8 b1 = *reinterpret_cast<const bf16x8*>(Ks + KSWZ(32 + r32, cb));
;     p0 = __builtin_amdgcn_mfma_f32_32x32x16_bf16(b0, qr[d0], p0, 0, 0, 0);
;     p1 = __builtin_amdgcn_mfma_f32_32x32x16_bf16(b1, qr[d0], p1, 0, 0, 0); }
; #pragma unroll
;   for (int d0 = 8; d0 < 12; ++d0) { int cb = (d0 * 16 + hi * 8) * 2;
;     bf16x8 b0 = *reinterpret_cast<const bf16x8*>(Ks + KSWZ(r32, cb));
;     bf16x8 b1 = *reinterpret_cast<const bf16x8*>(Ks + KSWZ(32 + r32, cb));
;     bf16x8 qf = *reinterpret_cast<const bf16x8*>(qrl + (((2 * (d0 - 8) + hi) ^ ((r32 >> 1) & 7)) << 4));
;     p0 = __builtin_amdgcn_mfma_f32_32x32x16_bf16(b0, qf, p0, 0, 0, 0);
;     p1 = __builtin_amdgcn_mfma_f32_32x32x16_bf16(b1, qf, p1, 0, 0, 0); }
; }
.Lattn_steady:
	v_exp_f32_e32 v225, v225
	v_exp_f32_e32 v228, v228
	v_exp_f32_e32 v226, v226
	v_add_f32_e32 v211, v225, v228
	s_waitcnt lgkmcnt(3)
	v_mfma_f32_32x32x16_bf16 v[80:95], v[236:239], v[124:127], 0
	ds_read_b128 v[236:239], v206 offset:49152
	v_exp_f32_e32 v229, v229
	v_add_f32_e32 v211, v226, v211
	v_exp_f32_e32 v227, v227
	v_add_f32_e32 v211, v229, v211
	v_mfma_f32_32x32x16_bf16 v[64:79], v[240:243], v[124:127], 0
	ds_read_b128 v[240:243], v208 offset:36864
	v_exp_f32_e32 v230, v230
	v_add_f32_e32 v211, v227, v211
	v_exp_f32_e32 v223, v223
	v_add_f32_e32 v211, v230, v211
	s_waitcnt lgkmcnt(3)
	v_mfma_f32_32x32x16_bf16 v[80:95], v[248:251], v[120:123], v[80:95]
	ds_read_b128 v[248:251], v208 offset:49152
	v_exp_f32_e32 v224, v224
	v_add_f32_e32 v211, v223, v211
	v_exp_f32_e32 v219, v219
	v_add_f32_e32 v211, v224, v211
	v_mfma_f32_32x32x16_bf16 v[64:79], v[244:247], v[120:123], v[64:79]
	ds_read_b128 v[244:247], v207 offset:36864
	v_exp_f32_e32 v221, v221
	v_add_f32_e32 v211, v219, v211
	v_exp_f32_e32 v220, v220
	v_add_f32_e32 v211, v221, v211
	s_waitcnt lgkmcnt(3)
	v_mfma_f32_32x32x16_bf16 v[80:95], v[232:235], v[116:119], v[80:95]
	ds_read_b128 v[232:235], v207 offset:49152
	v_exp_f32_e32 v222, v222
	v_add_f32_e32 v211, v220, v211
	v_exp_f32_e32 v215, v215
	v_add_f32_e32 v211, v222, v211
	v_mfma_f32_32x32x16_bf16 v[64:79], v[236:239], v[116:119], v[64:79]
	ds_read_b128 v[236:239], v204 offset:36864
	v_exp_f32_e32 v217, v217
	v_add_f32_e32 v211, v215, v211
	v_exp_f32_e32 v216, v216
	v_add_f32_e32 v211, v217, v211
	s_waitcnt lgkmcnt(3)
	v_mfma_f32_32x32x16_bf16 v[80:95], v[240:243], v[112:115], v[80:95]
	ds_read_b128 v[240:243], v204 offset:49152
	v_exp_f32_e32 v218, v218
	v_add_f32_e32 v211, v216, v211
	v_exp_f32_e32 v162, v162
	v_add_f32_e32 v211, v218, v211
	v_mfma_f32_32x32x16_bf16 v[64:79], v[248:251], v[112:115], v[64:79]
	ds_read_b128 v[248:251], v203 offset:36864
	v_exp_f32_e32 v163, v163
	v_exp_f32_e32 v160, v160
	v_exp_f32_e32 v161, v161
	s_waitcnt lgkmcnt(3)
	v_mfma_f32_32x32x16_bf16 v[80:95], v[244:247], v[108:111], v[80:95]
	ds_read_b128 v[244:247], v203 offset:49152
	v_exp_f32_e32 v158, v158
	v_exp_f32_e32 v159, v159
	v_exp_f32_e32 v156, v156
	v_mfma_f32_32x32x16_bf16 v[64:79], v[232:235], v[108:111], v[64:79]
	ds_read_b128 v[232:235], v200 offset:36864
	v_exp_f32_e32 v157, v157
	v_exp_f32_e32 v154, v154
	v_exp_f32_e32 v155, v155
	s_waitcnt lgkmcnt(3)
	v_mfma_f32_32x32x16_bf16 v[80:95], v[236:239], v[104:107], v[80:95]
	ds_read_b128 v[236:239], v200 offset:49152
	v_exp_f32_e32 v152, v152
	v_exp_f32_e32 v153, v153
	v_exp_f32_e32 v150, v150
	v_mfma_f32_32x32x16_bf16 v[64:79], v[240:243], v[104:107], v[64:79]
	ds_read_b128 v[240:243], v191 offset:36864
	v_exp_f32_e32 v151, v151
	v_exp_f32_e32 v148, v148
	v_exp_f32_e32 v149, v149
	s_waitcnt lgkmcnt(3)
	v_mfma_f32_32x32x16_bf16 v[80:95], v[248:251], v[100:103], v[80:95]
	ds_read_b128 v[248:251], v202 offset:49152
	v_add_f32_e32 v212, v162, v163
	v_add_f32_e32 v212, v160, v212
	v_add_f32_e32 v212, v161, v212
	v_add_f32_e32 v212, v158, v212
	v_add_f32_e32 v212, v159, v212
	v_add_f32_e32 v212, v156, v212
	v_mfma_f32_32x32x16_bf16 v[64:79], v[244:247], v[100:103], v[64:79]
	ds_read_b128 v[244:247], v182
	v_add_f32_e32 v212, v157, v212
	v_add_f32_e32 v212, v154, v212
	v_add_f32_e32 v212, v155, v212
	v_add_f32_e32 v212, v152, v212
	v_add_f32_e32 v212, v153, v212
	v_add_f32_e32 v212, v150, v212
	s_waitcnt lgkmcnt(3)
	v_mfma_f32_32x32x16_bf16 v[80:95], v[232:235], v[96:99], v[80:95]
	ds_read_b128 v[232:235], v198 offset:36864
	v_add_f32_e32 v212, v151, v212
	v_add_f32_e32 v212, v148, v212
	v_add_f32_e32 v212, v149, v212
	v_add_f32_e32 v211, v211, v212
	v_mov_b32_e32 v212, v211
	s_lshl_b32 s19, s18, 14
	v_add_u32_e32 v231, s19, v183
	s_waitcnt vmcnt(0)
	v_mfma_f32_32x32x16_bf16 v[64:79], v[236:239], v[96:99], v[64:79]
	ds_read_b128 v[236:239], v201 offset:49152
	ds_write_b128 v231, v[140:143]
	v_add_u32_e32 v140, s19, v184
	ds_write_b128 v140, v[144:147]
	ds_write_b128 v185, v[136:139] offset:12288
	ds_write_b128 v185, v[132:135] offset:24576
	s_mov_b32 s18, 0xfffa0000
	ds_write_b128 v186, v[128:131] offset:12288
	v_add_co_u32_e32 v128, vcc, s18, v168
	s_mov_b32 s18, 0xfffc0000
	s_nop 0
	s_waitcnt lgkmcnt(7)
; __device__ __forceinline__ void finishSM(f32x16& p0, f32x16& p1, float alpha, float& l_reg, bf16x8& pa0, bf16x8& pa1, bf16x8& pa2, bf16x8& pa3) {
;     ...
;   PK4(p0, 0, pa0); PK4(p0, 8, pa1); PK4(p1, 0, pa2); PK4(p1, 8, pa3);
;     ...
; }
; __device__ __forceinline__ void qkt(f32x16& p0, f32x16& p1, const char* Ks, const bf16x8* qr, const char* qrl, int r32, int hi) {
;   p0 = f32x16{}; p1 = f32x16{};
; #pragma unroll
;   for (int d0 = 0; d0 < 8; ++d0) { int cb = (d0 * 16 + hi * 8) * 2;
;     bf16x8 b0 = *reinterpret_cast<const bf16x8*>(Ks + KSWZ(r32, cb));
;     bf16x8 b1 = *reinterpret_cast<const bf16x8*>(Ks + KSWZ(32 + r32, cb));
;     p0 = __builtin_amdgcn_mfma_f32_32x32x16_bf16(b0, qr[d0], p0, 0, 0, 0);
;     p1 = __builtin_amdgcn_mfma_f32_32x32x16_bf16(b1, qr[d0], p1, 0, 0, 0); }
; #pragma unroll
;   for (int d0 = 8; d0 < 12; ++d0) { int cb = (d0 * 16 + hi * 8) * 2;
;     bf16x8 b0 = *reinterpret_cast<const bf16x8*>(Ks + KSWZ(r32, cb));
;     bf16x8 b1 = *reinterpret_cast<const bf16x8*>(Ks + KSWZ(32 + r32, cb));
;     bf16x8 qf = *reinterpret_cast<const bf16x8*>(qrl + (((2 * (d0 - 8) + hi) ^ ((r32 >> 1) & 7)) << 4));
;     p0 = __builtin_amdgcn_mfma_f32_32x32x16_bf16(b0, qf, p0, 0, 0, 0);
;     p1 = __builtin_amdgcn_mfma_f32_32x32x16_bf16(b1, qf, p1, 0, 0, 0); }
; }
; __device__ __forceinline__ int v_st(int k, int c) { const int kk = (k & ~0xC) | ((k & 4) << 1) | ((k & 8) >> 1); return ((kk >> 3) * 4 + (c >> 5)) * 512 + ((kk & 7) * 32 + (c & 31)) * 2; }
; __device__ __forceinline__ int v_rd_base(int lane) { return ((lane & 3) << 3) | (((lane >> 2) & 3) << 6) | (((lane >> 4) & 1) << 5) | (((lane >> 5) & 1) << 8); }
; template <int OFF> __device__ __forceinline__ s16x4 tr_read(int vb) {
;   s16x4 r; asm volatile("ds_read_b64_tr_b16 %0, %1 offset:%2" : "=&v"(r) : "v"(vb), "i"(OFF) : "memory"); return r;
; }
; template <int D0> __device__ __forceinline__ void pv_one(f32x16& od, int vb, bf16x8 pa0, bf16x8 pa1, bf16x8 pa2, bf16x8 pa3) {
;   const s16x4 l0 = tr_read<v_rd_off(D0, 0, 0)>(vb), h0 = tr_read<v_rd_off(D0, 0, 1)>(vb), l1 = tr_read<v_rd_off(D0, 1, 0)>(vb), h1 = tr_read<v_rd_off(D0, 1, 1)>(vb);
;   const s16x4 l2 = tr_read<v_rd_off(D0, 2, 0)>(vb), h2 = tr_read<v_rd_off(D0, 2, 1)>(vb), l3 = tr_read<v_rd_off(D0, 3, 0)>(vb), h3 = tr_read<v_rd_off(D0, 3, 1)>(vb);
;   asm volatile("s_waitcnt lgkmcnt(0)" ::: "memory"); SBAR();
	v_mfma_f32_32x32x16_bf16 v[80:95], v[240:243], v[244:247], v[80:95]
	ds_read_b128 v[240:243], v181
	v_addc_co_u32_e32 v129, vcc, -1, v169, vcc
	v_add_co_u32_e32 v130, vcc, s18, v168
	s_movk_i32 s18, 0xe000
	s_nop 0
	v_addc_co_u32_e32 v131, vcc, -1, v169, vcc
	global_load_dwordx4 v[140:143], v[128:129], off
	global_load_dwordx4 v[136:139], v[128:129], off offset:-256
	global_load_dwordx4 v[144:147], v[130:131], off
	v_mfma_f32_32x32x16_bf16 v[64:79], v[248:251], v[244:247], v[64:79]
	ds_read_b128 v[248:251], v187 offset:36864
	ds_read_b128 v[244:247], v189 offset:49152
	global_load_dwordx4 v[132:135], v[130:131], off offset:-256
	v_add_co_u32_e32 v128, vcc, s18, v166
	s_nop 1
	v_addc_co_u32_e32 v129, vcc, -1, v167, vcc
	global_load_dwordx4 v[128:131], v[128:129], off
	v_cvt_pk_bf16_f32 v158, v158, v159
	v_cvt_pk_bf16_f32 v159, v156, v157
	s_waitcnt lgkmcnt(2)
	v_mfma_f32_32x32x16_bf16 v[80:95], v[232:235], v[240:243], v[80:95]
	ds_read_b128 v[232:235], v179
	v_permlane32_swap_b32_e32 v211, v212
	v_cvt_pk_bf16_f32 v156, v162, v163
	v_cvt_pk_bf16_f32 v157, v160, v161
	v_cvt_pk_bf16_f32 v160, v154, v155
	v_cvt_pk_bf16_f32 v161, v152, v153
	v_cvt_pk_bf16_f32 v162, v150, v151
	v_mfma_f32_32x32x16_bf16 v[64:79], v[236:239], v[240:243], v[64:79]
	ds_read_b128 v[236:239], v188 offset:36864
	ds_read_b128 v[240:243], v190 offset:49152
	v_cvt_pk_bf16_f32 v163, v148, v149
	v_add_f32_e32 v211, v211, v212
	v_cvt_pk_bf16_f32 v148, v225, v228
	v_cvt_pk_bf16_f32 v149, v226, v229
	v_cvt_pk_bf16_f32 v150, v227, v230
	v_cvt_pk_bf16_f32 v151, v223, v224
	s_waitcnt lgkmcnt(2)
	v_mfma_f32_32x32x16_bf16 v[80:95], v[248:251], v[232:235], v[80:95]
	ds_read_b128 v[248:251], v177
	v_cvt_pk_bf16_f32 v152, v219, v221
	v_cvt_pk_bf16_f32 v153, v220, v222
	v_cvt_pk_bf16_f32 v154, v215, v217
	v_cvt_pk_bf16_f32 v155, v216, v218
	v_fma_f32 v176, v209, v176, v211
	v_mfma_f32_32x32x16_bf16 v[64:79], v[244:247], v[232:235], v[64:79]
	s_waitcnt lgkmcnt(0)
	v_mfma_f32_32x32x16_bf16 v[80:95], v[236:239], v[248:251], v[80:95]
	v_mfma_f32_32x32x16_bf16 v[64:79], v[240:243], v[248:251], v[64:79]
	s_lshl_b32 s31, s30, 14
	v_add_u32_e32 v180, s31, v178
	ds_read_b64_tr_b16 v[232:233], v180 offset:0
	ds_read_b64_tr_b16 v[234:235], v180 offset:2048
	ds_read_b64_tr_b16 v[236:237], v180 offset:512
	ds_read_b64_tr_b16 v[238:239], v180 offset:2560
	ds_read_b64_tr_b16 v[240:241], v180 offset:1024
	ds_read_b64_tr_b16 v[242:243], v180 offset:3072
	ds_read_b64_tr_b16 v[248:249], v180 offset:1536
	ds_read_b64_tr_b16 v[250:251], v180 offset:3584
	ds_read_b64_tr_b16 v[244:245], v180 offset:4096
	ds_read_b64_tr_b16 v[246:247], v180 offset:6144
	s_nop 3
	v_max3_f32 v194, v80, v81, v82
	v_max3_f32 v195, v64, v65, v66
	v_max3_f32 v194, v194, v83, v84
	v_max3_f32 v195, v195, v67, v68
	s_waitcnt lgkmcnt(6)
	v_mfma_f32_32x32x16_bf16 v[32:47], v[148:151], v[232:235], v[32:47]
	ds_read_b64_tr_b16 v[232:233], v180 offset:4608
	ds_read_b64_tr_b16 v[234:235], v180 offset:6656
	v_max3_f32 v194, v194, v85, v86
	v_max3_f32 v195, v195, v69, v70
	v_max3_f32 v194, v194, v87, v88
	v_max3_f32 v195, v195, v71, v72
	v_mfma_f32_32x32x16_bf16 v[48:63], v[148:151], v[236:239], v[48:63]
	ds_read_b64_tr_b16 v[236:237], v180 offset:5120
	ds_read_b64_tr_b16 v[238:239], v180 offset:7168
	v_max3_f32 v194, v194, v89, v90
	v_max3_f32 v195, v195, v73, v74
	v_max3_f32 v194, v194, v91, v92
	v_max3_f32 v195, v195, v75, v76
	s_waitcnt lgkmcnt(6)
	v_mfma_f32_32x32x16_bf16 v[16:31], v[148:151], v[240:243], v[16:31]
	ds_read_b64_tr_b16 v[240:241], v180 offset:5632
	ds_read_b64_tr_b16 v[242:243], v180 offset:7680
	v_max3_f32 v194, v194, v93, v94
	v_max3_f32 v195, v195, v77, v78
	v_max3_f32 v194, v194, v95, v195
	v_max_f32_e32 v194, v194, v79
	v_mfma_f32_32x32x16_bf16 v[0:15], v[148:151], v[248:251], v[0:15]
	ds_read_b64_tr_b16 v[248:249], v180 offset:8192
	ds_read_b64_tr_b16 v[250:251], v180 offset:10240
	v_mov_b32_e32 v195, v194
	s_nop 1
	v_permlane32_swap_b32_e32 v194, v195
	v_max_f32_e32 v194, v194, v195
	s_waitcnt lgkmcnt(6)
	v_mfma_f32_32x32x16_bf16 v[32:47], v[152:155], v[244:247], v[32:47]
	ds_read_b64_tr_b16 v[244:245], v180 offset:8704
	ds_read_b64_tr_b16 v[246:247], v180 offset:10752
	v_sub_f32_e32 v195, v194, v210
	v_cmp_ge_f32_e32 vcc, s15, v195
	v_mfma_f32_32x32x16_bf16 v[48:63], v[152:155], v[232:235], v[48:63]
	ds_read_b64_tr_b16 v[232:233], v180 offset:9216
	ds_read_b64_tr_b16 v[234:235], v180 offset:11264
	s_cmp_eq_u64 vcc, exec
	s_cselect_b64 s[40:41], -1, 0
	s_cbranch_scc1 .Lattn_fast1
	v_max_f32_e32 v194, v210, v194
	v_sub_f32_e32 v195, v210, v194
	v_mul_f32_e32 v195, 0x3dd53b94, v195
	v_exp_f32_e32 v214, v195
	v_mov_b32_e32 v210, v194
	s_branch .Lattn_join1

; #define SBAR() __builtin_amdgcn_sched_barrier(0)
; #define RESC(a) do { if (__any((a) < 1.f)) { if (hi == 0) al_l[r32] = (a); asm volatile("s_waitcnt lgkmcnt(0)" ::: "memory"); \
;     _Pragma("unroll") for (int d = 0; d < 4; ++d) _Pragma("unroll") for (int r = 0; r < 16; ++r) o[d][r] *= al_l[crow(r, hi)]; } } while (0)
; #define LBAR() do { asm volatile("s_waitcnt lgkmcnt(0)" ::: "memory"); __builtin_amdgcn_s_barrier(); asm volatile("" ::: "memory"); } while (0)
; __device__ __forceinline__ void attn_unit(const bf16_t* __restrict__ Qb, const bf16_t* __restrict__ Kn, const bf16_t* __restrict__ Vh, const bf16_t* __restrict__ Kr,
;                                           bf16_t* GO, int seq, char* lds, const int tid) {
;     ...
;   for (int j = 1; j + 1 < NT; j += 2) {
;     const int bp = bc == 0 ? 2 : bc - 1, bn = bc == 2 ? 0 : bc + 1;
;     SBAR(); qkt(pB0, pB1, K_lds + bc * SHM_K, qr, qrl, r32, hi);
;     finishSM(pA0, pA1, alA, l_reg, pa0, pa1, pa2, pa3); SBAR();
;     SWRITE(bn, 0); SLOAD(0, (j + 2) * KVBLK); SBAR();
;     pv_d0(o, vb0 + bp * SHM_V, pa0, pa1, pa2, pa3); partialSM(pB0, pB1, m_reg, mnB, alB);
;     RESC(alB); LBAR();
;     SBAR(); qkt(pA0, pA1, K_lds + bn * SHM_K, qr, qrl, r32, hi);
;     finishSM(pB0, pB1, alB, l_reg, pa0, pa1, pa2, pa3); SBAR();
;     SWRITE(bp, 0); if (j + 3 < NT) SLOAD(0, (j + 3) * KVBLK); SBAR();
;     pv_d0(o, vb0 + bc * SHM_V, pa0, pa1, pa2, pa3); partialSM(pA0, pA1, m_reg, mnA, alA);
;     RESC(alA); LBAR();
;     bc = bp;
;   }
.Lattn_skip_rs2:
	s_and_b64 vcc, exec, s[28:29]
	s_cbranch_vccnz .LBB0_1163
	s_mov_b32 s76, s30
	s_mov_b32 s30, s100
	s_mov_b32 s18, s101
	v_mov_b32_e32 v209, v213
	s_branch .Lattn_steady

; __global__ void __launch_bounds__(NTHR, 2) mk_fwd(Params Punused) {
	.amdhsa_kernel _Z6mk_fwd6Params
		.amdhsa_group_segment_fixed_size 0
		.amdhsa_private_segment_fixed_size 0
		.amdhsa_kernarg_size 416
		.amdhsa_user_sgpr_count 2
		.amdhsa_user_sgpr_dispatch_ptr 0
		.amdhsa_user_sgpr_queue_ptr 0
		.amdhsa_user_sgpr_kernarg_segment_ptr 1
		.amdhsa_user_sgpr_dispatch_id 0
		.amdhsa_user_sgpr_kernarg_preload_length 0
		.amdhsa_user_sgpr_kernarg_preload_offset 0
		.amdhsa_user_sgpr_private_segment_size 0
		.amdhsa_uses_dynamic_stack 0
		.amdhsa_enable_private_segment 0
		.amdhsa_system_sgpr_workgroup_id_x 1
		.amdhsa_system_sgpr_workgroup_id_y 0
		.amdhsa_system_sgpr_workgroup_id_z 0
		.amdhsa_system_sgpr_workgroup_info 0
		.amdhsa_system_vgpr_workitem_id 2
		.amdhsa_next_free_vgpr 256
		.amdhsa_next_free_sgpr 102
		.amdhsa_accum_offset 256
		.amdhsa_reserve_vcc 1
		.amdhsa_float_round_mode_32 0
		.amdhsa_float_round_mode_16_64 0
		.amdhsa_float_denorm_mode_32 3
		.amdhsa_float_denorm_mode_16_64 3
		.amdhsa_dx10_clamp 1
		.amdhsa_ieee_mode 1
		.amdhsa_fp16_overflow 0
		.amdhsa_tg_split 0
		.amdhsa_exception_fp_ieee_invalid_op 0
		.amdhsa_exception_fp_denorm_src 0
		.amdhsa_exception_fp_ieee_div_zero 0
		.amdhsa_exception_fp_ieee_overflow 0
		.amdhsa_exception_fp_ieee_underflow 0
		.amdhsa_exception_fp_ieee_inexact 0
		.amdhsa_exception_int_div_zero 0
	.end_amdhsa_kernel

; __global__ void __launch_bounds__(NTHR, 2) mk_fwd(Params Punused) {
amdhsa.kernels:
  - .agpr_count:     0
    .args:
      - .offset:         0
        .size:           160
        .value_kind:     by_value
      - .offset:         160
        .size:           4
        .value_kind:     hidden_block_count_x
      - .offset:         164
        .size:           4
        .value_kind:     hidden_block_count_y
      - .offset:         168
        .size:           4
        .value_kind:     hidden_block_count_z
      - .offset:         172
        .size:           2
        .value_kind:     hidden_group_size_x
      - .offset:         174
        .size:           2
        .value_kind:     hidden_group_size_y
      - .offset:         176
        .size:           2
        .value_kind:     hidden_group_size_z
      - .offset:         178
        .size:           2
        .value_kind:     hidden_remainder_x
      - .offset:         180
        .size:           2
        .value_kind:     hidden_remainder_y
      - .offset:         182
        .size:           2
        .value_kind:     hidden_remainder_z
      - .offset:         200
        .size:           8
        .value_kind:     hidden_global_offset_x
      - .offset:         208
        .size:           8
        .value_kind:     hidden_global_offset_y
      - .offset:         216
        .size:           8
        .value_kind:     hidden_global_offset_z
      - .offset:         224
        .size:           2
        .value_kind:     hidden_grid_dims
      - .offset:         248
        .size:           8
        .value_kind:     hidden_multigrid_sync_arg
      - .offset:         280
        .size:           4
        .value_kind:     hidden_dynamic_lds_size
    .group_segment_fixed_size: 0
    .kernarg_segment_align: 8
    .kernarg_segment_size: 416
    .language:       OpenCL C
    .language_version:
      - 2
      - 0
    .max_flat_workgroup_size: 512
    .name:           _Z6mk_fwd6Params
    .private_segment_fixed_size: 0
    .sgpr_count:     108
    .sgpr_spill_count: 133
    .symbol:         _Z6mk_fwd6Params.kd
    .uniform_work_group_size: 1
    .uses_dynamic_stack: false
    .vgpr_count:     256
    .vgpr_spill_count: 0
    .wavefront_size: 64
